# speedup vs baseline: 1.0019x; 1.0019x over previous
; __device__ __forceinline__ int crow(int r, int hi) { return (r & 3) + 8 * (r >> 2) + 4 * hi; }
; __device__ __forceinline__ unsigned cvtpk(float lo, float hi) { unsigned r; asm volatile("v_cvt_pk_bf16_f32 %0, %1, %2" : "=v"(r) : "v"(lo), "v"(hi)); return r; }
; __device__ __forceinline__ void unit_dma(const bf16* __restrict__ Qb, const bf16* __restrict__ Kh, const bf16* __restrict__ Vh, bf16* __restrict__ Ob, char* lds, LAS unsigned char* ldsL, int wave_s, float mref) {
;     ...
;     if (hi == 0) li_l[r32] = l_reg; asm volatile("s_waitcnt lgkmcnt(0)" ::: "memory");
;     float rli[16];
; #pragma unroll
;     for (int r = 0; r < 16; ++r) rli[r] = __builtin_amdgcn_rcpf(li_l[crow(r, hi)]);
;     bf16* Ow = Ob + (long)(wid * QBLK) * 1024;
; #pragma unroll
;     for (int r = 0; r < 16; ++r) { const int orow = crow(r, hi);
; #pragma unroll
;         for (int d0 = 0; d0 < 4; ++d0) Ow[(long)orow * 1024 + d0 * 32 + r32] = (bf16)(cvtpk(o[d0][r] * rli[r], 0.f) & 0xffffu); }
.LBB0_166:
	s_or_b64 exec, exec, s[22:23]
	s_waitcnt lgkmcnt(0)
	v_add_u32_e32 v72, s89, v148
	ds_read_b128 v[64:67], v72
	ds_read_b128 v[68:71], v72 offset:32
	s_ashr_i32 s75, s74, 31
	s_lshl_b64 s[18:19], s[74:75], 19
	s_add_u32 s3, s24, s18
	s_addc_u32 s5, s25, s19
	s_lshl_b32 s18, s79, 8
	s_waitcnt lgkmcnt(0)
	v_rcp_f32_e32 v73, v64
	v_rcp_f32_e32 v74, v65
	v_rcp_f32_e32 v75, v66
	v_rcp_f32_e32 v76, v67
	ds_read_b128 v[64:67], v72 offset:64
	s_add_u32 s3, s3, s18
	s_addc_u32 s5, s5, 0
	v_readlane_b32 s0, v253, 18
	v_readlane_b32 s1, v253, 19
	s_add_u32 s18, s3, s0
	s_addc_u32 s19, s5, s1
	v_lshlrev_b32_e32 v148, 1, v212
	v_rcp_f32_e32 v77, v68
	v_rcp_f32_e32 v78, v69
	v_rcp_f32_e32 v79, v70
	v_rcp_f32_e32 v80, v71
	ds_read_b128 v[68:71], v72 offset:96
	s_waitcnt lgkmcnt(0)
	v_rcp_f32_e32 v72, v64
	v_rcp_f32_e32 v81, v65
	v_rcp_f32_e32 v82, v66
	v_rcp_f32_e32 v83, v67
	v_rcp_f32_e32 v68, v68
	v_rcp_f32_e32 v69, v69
	v_rcp_f32_e32 v70, v70
	v_rcp_f32_e32 v71, v71
	v_readlane_b32 s0, v254, 58
	v_lshlrev_b32_e32 v84, 10, v213
	v_lshl_add_u32 v84, v212, 1, v84
	s_lshl_b32 s0, s0, 13
	v_add_u32_e32 v84, s0, v84
	v_lshl_add_u32 v85, v196, 4, s0
	v_mul_f32_e32 v0, v0, v73
	v_mul_f32_e32 v48, v48, v73
	v_mul_f32_e32 v32, v32, v73
	v_mul_f32_e32 v16, v16, v73
	v_cvt_pk_bf16_f32 v0, v0, v48
	v_cvt_pk_bf16_f32 v32, v32, v16
	s_nop 0
	ds_write_b16 v84, v0 offset:0
	ds_write_b16_d16_hi v84, v0 offset:64
	ds_write_b16 v84, v32 offset:128
	ds_write_b16_d16_hi v84, v32 offset:192
	v_mul_f32_e32 v1, v1, v74
	v_mul_f32_e32 v49, v49, v74
	v_mul_f32_e32 v33, v33, v74
	v_mul_f32_e32 v17, v17, v74
	v_cvt_pk_bf16_f32 v1, v1, v49
	v_cvt_pk_bf16_f32 v33, v33, v17
	s_nop 0
	ds_write_b16 v84, v1 offset:256
	ds_write_b16_d16_hi v84, v1 offset:320
	ds_write_b16 v84, v33 offset:384
	ds_write_b16_d16_hi v84, v33 offset:448
	v_mul_f32_e32 v2, v2, v75
	v_mul_f32_e32 v50, v50, v75
	v_mul_f32_e32 v34, v34, v75
	v_mul_f32_e32 v18, v18, v75
	v_cvt_pk_bf16_f32 v2, v2, v50
	v_cvt_pk_bf16_f32 v34, v34, v18
	s_nop 0
	ds_write_b16 v84, v2 offset:512
	ds_write_b16_d16_hi v84, v2 offset:576
	ds_write_b16 v84, v34 offset:640
	ds_write_b16_d16_hi v84, v34 offset:704
	v_mul_f32_e32 v3, v3, v76
	v_mul_f32_e32 v51, v51, v76
	v_mul_f32_e32 v35, v35, v76
	v_mul_f32_e32 v19, v19, v76
	v_cvt_pk_bf16_f32 v3, v3, v51
	v_cvt_pk_bf16_f32 v35, v35, v19
	s_nop 0
	ds_write_b16 v84, v3 offset:768
	ds_write_b16_d16_hi v84, v3 offset:832
	ds_write_b16 v84, v35 offset:896
	ds_write_b16_d16_hi v84, v35 offset:960
	v_mul_f32_e32 v4, v4, v77
	v_mul_f32_e32 v52, v52, v77
	v_mul_f32_e32 v36, v36, v77
	v_mul_f32_e32 v20, v20, v77
	v_cvt_pk_bf16_f32 v4, v4, v52
	v_cvt_pk_bf16_f32 v36, v36, v20
	s_nop 0
	ds_write_b16 v84, v4 offset:2048
	ds_write_b16_d16_hi v84, v4 offset:2112
	ds_write_b16 v84, v36 offset:2176
	ds_write_b16_d16_hi v84, v36 offset:2240
	v_mul_f32_e32 v5, v5, v78
	v_mul_f32_e32 v53, v53, v78
	v_mul_f32_e32 v37, v37, v78
	v_mul_f32_e32 v21, v21, v78
	v_cvt_pk_bf16_f32 v5, v5, v53
	v_cvt_pk_bf16_f32 v37, v37, v21
	s_nop 0
	ds_write_b16 v84, v5 offset:2304
	ds_write_b16_d16_hi v84, v5 offset:2368
	ds_write_b16 v84, v37 offset:2432
	ds_write_b16_d16_hi v84, v37 offset:2496
	v_mul_f32_e32 v6, v6, v79
	v_mul_f32_e32 v54, v54, v79
	v_mul_f32_e32 v38, v38, v79
	v_mul_f32_e32 v22, v22, v79
	v_cvt_pk_bf16_f32 v6, v6, v54
	v_cvt_pk_bf16_f32 v38, v38, v22
	s_nop 0
	ds_write_b16 v84, v6 offset:2560
	ds_write_b16_d16_hi v84, v6 offset:2624
	ds_write_b16 v84, v38 offset:2688
	ds_write_b16_d16_hi v84, v38 offset:2752
	v_mul_f32_e32 v7, v7, v80
	v_mul_f32_e32 v55, v55, v80
	v_mul_f32_e32 v39, v39, v80
	v_mul_f32_e32 v23, v23, v80
	v_cvt_pk_bf16_f32 v7, v7, v55
	v_cvt_pk_bf16_f32 v39, v39, v23
	s_nop 0
	ds_write_b16 v84, v7 offset:2816
	ds_write_b16_d16_hi v84, v7 offset:2880
	ds_write_b16 v84, v39 offset:2944
	ds_write_b16_d16_hi v84, v39 offset:3008
	v_mul_f32_e32 v8, v8, v72
	v_mul_f32_e32 v56, v56, v72
	v_mul_f32_e32 v40, v40, v72
	v_mul_f32_e32 v24, v24, v72
	v_cvt_pk_bf16_f32 v8, v8, v56
	v_cvt_pk_bf16_f32 v40, v40, v24
	s_nop 0
	ds_write_b16 v84, v8 offset:4096
	ds_write_b16_d16_hi v84, v8 offset:4160
	ds_write_b16 v84, v40 offset:4224
	ds_write_b16_d16_hi v84, v40 offset:4288
	v_mul_f32_e32 v9, v9, v81
	v_mul_f32_e32 v57, v57, v81
	v_mul_f32_e32 v41, v41, v81
	v_mul_f32_e32 v25, v25, v81
	v_cvt_pk_bf16_f32 v9, v9, v57
	v_cvt_pk_bf16_f32 v41, v41, v25
	s_nop 0
	ds_write_b16 v84, v9 offset:4352
	ds_write_b16_d16_hi v84, v9 offset:4416
	ds_write_b16 v84, v41 offset:4480
	ds_write_b16_d16_hi v84, v41 offset:4544
	v_mul_f32_e32 v10, v10, v82
	v_mul_f32_e32 v58, v58, v82
	v_mul_f32_e32 v42, v42, v82
	v_mul_f32_e32 v26, v26, v82
	v_cvt_pk_bf16_f32 v10, v10, v58
	v_cvt_pk_bf16_f32 v42, v42, v26
	s_nop 0
	ds_write_b16 v84, v10 offset:4608
	ds_write_b16_d16_hi v84, v10 offset:4672
	ds_write_b16 v84, v42 offset:4736
	ds_write_b16_d16_hi v84, v42 offset:4800
	v_mul_f32_e32 v11, v11, v83
	v_mul_f32_e32 v59, v59, v83
	v_mul_f32_e32 v43, v43, v83
	v_mul_f32_e32 v27, v27, v83
	v_cvt_pk_bf16_f32 v11, v11, v59
	v_cvt_pk_bf16_f32 v43, v43, v27
	s_nop 0
	ds_write_b16 v84, v11 offset:4864
	ds_write_b16_d16_hi v84, v11 offset:4928
	ds_write_b16 v84, v43 offset:4992
	ds_write_b16_d16_hi v84, v43 offset:5056
	v_mul_f32_e32 v12, v12, v68
	v_mul_f32_e32 v60, v60, v68
	v_mul_f32_e32 v44, v44, v68
	v_mul_f32_e32 v28, v28, v68
	v_cvt_pk_bf16_f32 v12, v12, v60
	v_cvt_pk_bf16_f32 v44, v44, v28
	s_nop 0
	ds_write_b16 v84, v12 offset:6144
	ds_write_b16_d16_hi v84, v12 offset:6208
	ds_write_b16 v84, v44 offset:6272
	ds_write_b16_d16_hi v84, v44 offset:6336
	v_mul_f32_e32 v13, v13, v69
	v_mul_f32_e32 v61, v61, v69
	v_mul_f32_e32 v45, v45, v69
	v_mul_f32_e32 v29, v29, v69
	v_cvt_pk_bf16_f32 v13, v13, v61
	v_cvt_pk_bf16_f32 v45, v45, v29
	s_nop 0
	ds_write_b16 v84, v13 offset:6400
	ds_write_b16_d16_hi v84, v13 offset:6464
	ds_write_b16 v84, v45 offset:6528
	ds_write_b16_d16_hi v84, v45 offset:6592
	v_mul_f32_e32 v14, v14, v70
	v_mul_f32_e32 v62, v62, v70
	v_mul_f32_e32 v46, v46, v70
	v_mul_f32_e32 v30, v30, v70
	v_cvt_pk_bf16_f32 v14, v14, v62
	v_cvt_pk_bf16_f32 v46, v46, v30
	s_nop 0
	ds_write_b16 v84, v14 offset:6656
	ds_write_b16_d16_hi v84, v14 offset:6720
	ds_write_b16 v84, v46 offset:6784
	ds_write_b16_d16_hi v84, v46 offset:6848
	v_mul_f32_e32 v15, v15, v71
	v_mul_f32_e32 v63, v63, v71
	v_mul_f32_e32 v47, v47, v71
	v_mul_f32_e32 v31, v31, v71
	v_cvt_pk_bf16_f32 v15, v15, v63
	v_cvt_pk_bf16_f32 v47, v47, v31
	s_nop 0
	ds_write_b16 v84, v15 offset:6912
	ds_write_b16_d16_hi v84, v15 offset:6976
	ds_write_b16 v84, v47 offset:7040
	ds_write_b16_d16_hi v84, v47 offset:7104
	v_lshrrev_b32_e32 v86, 4, v196
	v_and_b32_e32 v87, 15, v196
	v_lshlrev_b32_e32 v86, 11, v86
	v_lshl_add_u32 v86, v87, 4, v86
	v_mov_b32_e32 v87, v149
	v_lshl_add_u64 v[86:87], s[18:19], 0, v[86:87]
	s_mov_b64 s[22:23], 0x2000
	s_waitcnt lgkmcnt(0)
; __device__ __forceinline__ int crow(int r, int hi) { return (r & 3) + 8 * (r >> 2) + 4 * hi; }
; __device__ __forceinline__ unsigned cvtpk(float lo, float hi) { unsigned r; asm volatile("v_cvt_pk_bf16_f32 %0, %1, %2" : "=v"(r) : "v"(lo), "v"(hi)); return r; }
; __device__ __forceinline__ void unit_dma(const bf16* __restrict__ Qb, const bf16* __restrict__ Kh, const bf16* __restrict__ Vh, bf16* __restrict__ Ob, char* lds, LAS unsigned char* ldsL, int wave_s, float mref) {
;     ...
;     bf16* Ow = Ob + (long)(wid * QBLK) * 1024;
; #pragma unroll
;     for (int r = 0; r < 16; ++r) { const int orow = crow(r, hi);
; #pragma unroll
;         for (int d0 = 0; d0 < 4; ++d0) Ow[(long)orow * 1024 + d0 * 32 + r32] = (bf16)(cvtpk(o[d0][r] * rli[r], 0.f) & 0xffffu); }
;     asm volatile("s_waitcnt vmcnt(0) lgkmcnt(0)\n\ts_barrier" ::: "memory");
	ds_read_b128 v[96:99], v85
	ds_read_b128 v[100:103], v85 offset:1024
	ds_read_b128 v[104:107], v85 offset:2048
	ds_read_b128 v[108:111], v85 offset:3072
	ds_read_b128 v[112:115], v85 offset:4096
	ds_read_b128 v[116:119], v85 offset:5120
	ds_read_b128 v[120:123], v85 offset:6144
	ds_read_b128 v[124:127], v85 offset:7168
	s_waitcnt lgkmcnt(7)
	global_store_dwordx4 v[86:87], v[96:99], off
	v_lshl_add_u64 v[86:87], v[86:87], 0, s[22:23]
	s_waitcnt lgkmcnt(6)
	global_store_dwordx4 v[86:87], v[100:103], off
	v_lshl_add_u64 v[86:87], v[86:87], 0, s[22:23]
	s_waitcnt lgkmcnt(5)
	global_store_dwordx4 v[86:87], v[104:107], off
	v_lshl_add_u64 v[86:87], v[86:87], 0, s[22:23]
	s_waitcnt lgkmcnt(4)
	global_store_dwordx4 v[86:87], v[108:111], off
	v_lshl_add_u64 v[86:87], v[86:87], 0, s[22:23]
	s_waitcnt lgkmcnt(3)
	global_store_dwordx4 v[86:87], v[112:115], off
	v_lshl_add_u64 v[86:87], v[86:87], 0, s[22:23]
	s_waitcnt lgkmcnt(2)
	global_store_dwordx4 v[86:87], v[116:119], off
	v_lshl_add_u64 v[86:87], v[86:87], 0, s[22:23]
	s_waitcnt lgkmcnt(1)
	global_store_dwordx4 v[86:87], v[120:123], off
	v_lshl_add_u64 v[86:87], v[86:87], 0, s[22:23]
	s_waitcnt lgkmcnt(0)
	global_store_dwordx4 v[86:87], v[124:127], off
	s_waitcnt vmcnt(0) lgkmcnt(0)
	s_barrier
	s_add_i32 s78, s78, s15
	s_add_i32 s73, s73, s15
	s_cmpk_lt_i32 s78, 0x100
	s_cbranch_scc0 .LBB0_200
